# grid-wide split-phase counters polled once early, in the shadow of the group sync
# baseline (speedup 1.0000x reference)
; __device__ __forceinline__ unsigned xb_ld(unsigned* p)              { return __hip_atomic_load(p, __ATOMIC_RELAXED, __HIP_MEMORY_SCOPE_AGENT); }
; __device__ __forceinline__ unsigned xb_add(unsigned* p, unsigned v) { return __hip_atomic_fetch_add(p, v, __ATOMIC_RELAXED, __HIP_MEMORY_SCOPE_AGENT); }
; #define XB_SPIN(cond, bar) do { unsigned _sp = 0; while (cond) { __builtin_amdgcn_s_sleep(1); \
;     if ((++_sp & 255u) == 0u) { if (xb_ld(&(bar)[XB_TMO])) break; if (_sp > XB_SPIN_CAP) { atomicAdd(&(bar)[XB_TMO], 1u); break; } } } } while (0)
; __device__ __forceinline__ void xcd_barrier(const XcdBarrier& b) {
;     ...
;     if (threadIdx.x == 0) {
;         unsigned* bar = b.bar;
;         __builtin_amdgcn_s_waitcnt(0);
;         unsigned nloc = b.st[0], nx = b.st[1];
;         if (nloc == 0u) { xcd_barrier_complete(bar, b.x, nloc, nx); b.st[0] = nloc; b.st[1] = nx; }
;         const unsigned old = xb_add(&bar[XB_XSUB(b.x)], 1u);
;         const unsigned gen = old / nloc;
;         if (old + 1u == (gen + 1u) * nloc) {
;             __builtin_amdgcn_fence(__ATOMIC_RELEASE, "agent");
;             asm volatile("s_waitcnt vmcnt(0)" ::: "memory");
;             const unsigned og = xb_add(&bar[XB_TOP], 1u);
;             const unsigned tg = og / nx;
;             if (og + 1u == (tg + 1u) * nx) xb_add(&bar[XB_TOPGEN], 1u);
;             else XB_SPIN(xb_ld(&bar[XB_TOPGEN]) == tg, bar);
;             __builtin_amdgcn_fence(__ATOMIC_ACQUIRE, "agent");
;             xb_add(&bar[XB_XGEN(b.x)], 1u);
;             asm volatile("s_waitcnt vmcnt(0)" ::: "memory");
;         } else {
;             XB_SPIN(xb_ld(&bar[XB_XGEN(b.x)]) == gen, bar);
.LBB0_517:
	s_waitcnt vmcnt(0)
	s_barrier
	s_mov_b64 s[2:3], exec
	v_readlane_b32 s12, v253, 36
	v_readlane_b32 s13, v253, 37
	s_and_b64 s[12:13], s[2:3], s[12:13]
	s_mov_b64 exec, s[12:13]
	s_cbranch_execz .LBB0_569
	s_cmp_lg_u32 s98, 0
	s_cbranch_scc0 .Lgb_full_569
	v_readlane_b32 s4, v253, 1
	v_readlane_b32 s12, v253, 56
	v_readlane_b32 s13, v253, 57
	s_add_i32 s99, s99, 4
	s_nop 2
	s_and_b32 s4, s4, 63
	s_lshl_b32 s4, s4, 7
	s_add_i32 s4, s4, 0x3e00
	v_mov_b32_e32 v2, s4
	s_mov_b32 s1, 0
	s_nop 1
	global_atomic_add v5, v2, v234, s[12:13] sc0
	v_mov_b32_e32 v7, 0x5e00
	global_load_dword v6, v7, s[12:13] sc1
	s_waitcnt vmcnt(1)
	v_readfirstlane_b32 s4, v5
	s_nop 3
	s_add_i32 s4, s4, 1
	s_cmp_ge_u32 s4, s99
	s_cbranch_scc1 .Lgb_grp_ok_569

; __device__ __forceinline__ unsigned xb_ld(unsigned* p)              { return __hip_atomic_load(p, __ATOMIC_RELAXED, __HIP_MEMORY_SCOPE_AGENT); }
; __device__ __forceinline__ unsigned xb_add(unsigned* p, unsigned v) { return __hip_atomic_fetch_add(p, v, __ATOMIC_RELAXED, __HIP_MEMORY_SCOPE_AGENT); }
; #define XB_SPIN(cond, bar) do { unsigned _sp = 0; while (cond) { __builtin_amdgcn_s_sleep(1); \
;     if ((++_sp & 255u) == 0u) { if (xb_ld(&(bar)[XB_TMO])) break; if (_sp > XB_SPIN_CAP) { atomicAdd(&(bar)[XB_TMO], 1u); break; } } } } while (0)
; __device__ __forceinline__ void xcd_barrier(const XcdBarrier& b) {
;     ...
;         const unsigned old = xb_add(&bar[XB_XSUB(b.x)], 1u);
;         const unsigned gen = old / nloc;
;         if (old + 1u == (gen + 1u) * nloc) {
;             __builtin_amdgcn_fence(__ATOMIC_RELEASE, "agent");
;             asm volatile("s_waitcnt vmcnt(0)" ::: "memory");
;             const unsigned og = xb_add(&bar[XB_TOP], 1u);
;             const unsigned tg = og / nx;
;             if (og + 1u == (tg + 1u) * nx) xb_add(&bar[XB_TOPGEN], 1u);
;             else XB_SPIN(xb_ld(&bar[XB_TOPGEN]) == tg, bar);
;             __builtin_amdgcn_fence(__ATOMIC_ACQUIRE, "agent");
;             xb_add(&bar[XB_XGEN(b.x)], 1u);
;             asm volatile("s_waitcnt vmcnt(0)" ::: "memory");
;         } else {
;             XB_SPIN(xb_ld(&bar[XB_XGEN(b.x)]) == gen, bar);
.Lgb_grp_ok_569:
	v_mov_b32_e32 v4, 0x5e00
	s_lshl_b32 s16, s92, 8
	s_add_i32 s16, s16, 0x100
	s_waitcnt vmcnt(0)
	v_readfirstlane_b32 s17, v6
	s_nop 3
	s_cmp_ge_u32 s17, s16
	s_cbranch_scc1 .Lgb_p3_ok_569

; __device__ __forceinline__ unsigned xb_ld(unsigned* p)              { return __hip_atomic_load(p, __ATOMIC_RELAXED, __HIP_MEMORY_SCOPE_AGENT); }
; __device__ __forceinline__ unsigned xb_add(unsigned* p, unsigned v) { return __hip_atomic_fetch_add(p, v, __ATOMIC_RELAXED, __HIP_MEMORY_SCOPE_AGENT); }
; #define XB_SPIN(cond, bar) do { unsigned _sp = 0; while (cond) { __builtin_amdgcn_s_sleep(1); \
;     if ((++_sp & 255u) == 0u) { if (xb_ld(&(bar)[XB_TMO])) break; if (_sp > XB_SPIN_CAP) { atomicAdd(&(bar)[XB_TMO], 1u); break; } } } } while (0)
; __device__ __forceinline__ void xcd_barrier(const XcdBarrier& b) {
;     ...
;     if (threadIdx.x == 0) {
;         unsigned* bar = b.bar;
;         __builtin_amdgcn_s_waitcnt(0);
;         unsigned nloc = b.st[0], nx = b.st[1];
;         if (nloc == 0u) { xcd_barrier_complete(bar, b.x, nloc, nx); b.st[0] = nloc; b.st[1] = nx; }
;         const unsigned old = xb_add(&bar[XB_XSUB(b.x)], 1u);
;         const unsigned gen = old / nloc;
;         if (old + 1u == (gen + 1u) * nloc) {
;             __builtin_amdgcn_fence(__ATOMIC_RELEASE, "agent");
;             asm volatile("s_waitcnt vmcnt(0)" ::: "memory");
;             const unsigned og = xb_add(&bar[XB_TOP], 1u);
;             const unsigned tg = og / nx;
;             if (og + 1u == (tg + 1u) * nx) xb_add(&bar[XB_TOPGEN], 1u);
;             else XB_SPIN(xb_ld(&bar[XB_TOPGEN]) == tg, bar);
;             __builtin_amdgcn_fence(__ATOMIC_ACQUIRE, "agent");
;             xb_add(&bar[XB_XGEN(b.x)], 1u);
;             asm volatile("s_waitcnt vmcnt(0)" ::: "memory");
;         } else {
;             XB_SPIN(xb_ld(&bar[XB_XGEN(b.x)]) == gen, bar);
.LBB0_708:
	s_waitcnt vmcnt(0)
	s_barrier
	s_mov_b64 s[16:17], exec
	v_readlane_b32 s12, v253, 36
	v_readlane_b32 s13, v253, 37
	s_and_b64 s[12:13], s[16:17], s[12:13]
	s_mov_b64 exec, s[12:13]
	s_cbranch_execz .LBB0_137
	s_cmp_lg_u32 s98, 0
	s_cbranch_scc0 .Lgb_full_137
	v_readlane_b32 s4, v253, 1
	v_readlane_b32 s12, v253, 56
	v_readlane_b32 s13, v253, 57
	s_add_i32 s99, s99, 4
	s_nop 2
	s_and_b32 s4, s4, 63
	s_lshl_b32 s4, s4, 7
	s_add_i32 s4, s4, 0x3e00
	v_mov_b32_e32 v2, s4
	s_mov_b32 s1, 0
	s_nop 1
	global_atomic_add v5, v2, v234, s[12:13] sc0
	v_mov_b32_e32 v4, 0x5e80
	global_atomic_add v4, v234, s[12:13]
	v_mov_b32_e32 v7, 0x5ec0
	global_load_dword v6, v7, s[12:13] sc1
	s_waitcnt vmcnt(2)
	v_readfirstlane_b32 s4, v5
	s_nop 3
	s_add_i32 s4, s4, 1
	s_cmp_ge_u32 s4, s99
	s_cbranch_scc1 .Lgb_grp_ok_137

; __device__ __forceinline__ unsigned xb_ld(unsigned* p)              { return __hip_atomic_load(p, __ATOMIC_RELAXED, __HIP_MEMORY_SCOPE_AGENT); }
; __device__ __forceinline__ unsigned xb_add(unsigned* p, unsigned v) { return __hip_atomic_fetch_add(p, v, __ATOMIC_RELAXED, __HIP_MEMORY_SCOPE_AGENT); }
; #define XB_SPIN(cond, bar) do { unsigned _sp = 0; while (cond) { __builtin_amdgcn_s_sleep(1); \
;     if ((++_sp & 255u) == 0u) { if (xb_ld(&(bar)[XB_TMO])) break; if (_sp > XB_SPIN_CAP) { atomicAdd(&(bar)[XB_TMO], 1u); break; } } } } while (0)
; __device__ __forceinline__ void xcd_barrier(const XcdBarrier& b) {
;     ...
;         const unsigned old = xb_add(&bar[XB_XSUB(b.x)], 1u);
;         const unsigned gen = old / nloc;
;         if (old + 1u == (gen + 1u) * nloc) {
;             __builtin_amdgcn_fence(__ATOMIC_RELEASE, "agent");
;             asm volatile("s_waitcnt vmcnt(0)" ::: "memory");
;             const unsigned og = xb_add(&bar[XB_TOP], 1u);
;             const unsigned tg = og / nx;
;             if (og + 1u == (tg + 1u) * nx) xb_add(&bar[XB_TOPGEN], 1u);
;             else XB_SPIN(xb_ld(&bar[XB_TOPGEN]) == tg, bar);
;             __builtin_amdgcn_fence(__ATOMIC_ACQUIRE, "agent");
;             xb_add(&bar[XB_XGEN(b.x)], 1u);
;             asm volatile("s_waitcnt vmcnt(0)" ::: "memory");
;         } else {
;             XB_SPIN(xb_ld(&bar[XB_XGEN(b.x)]) == gen, bar);
.Lgb_grp_ok_137:
	v_mov_b32_e32 v4, 0x5ec0
	s_lshl_b32 s18, s92, 8
	s_add_i32 s18, s18, 0x100
	s_waitcnt vmcnt(0)
	v_readfirstlane_b32 s19, v6
	s_nop 3
	s_cmp_ge_u32 s19, s18
	s_cbranch_scc1 .Lgb_cv_ok_137
